# c5 + packed v_pk_add_f32 (negated broadcast mean) instead of 4 scalar v_sub_f32 in the hand-written EpiRes epilogues
# speedup vs baseline: 1.0024x; 1.0024x over previous
;     __device__ __forceinline__ void operator()(const f32x4 (&acc)[2][2][4][2], const Unit& u, int wr, int wc, int fr, int fq) const {
;         const int row0 = u.pm * BM + wr * 64 + fr; const int col0 = u.pn * BM + wc * 32 + 4 * fq;
; #pragma unroll
;         for (int bj = 0; bj < 2; ++bj)
; #pragma unroll
;             for (int n = 0; n < 2; ++n) {
;                 const int col = col0 + bj * HALF + n * 16;
;                 f32x4 gg = {1.f, 1.f, 1.f, 1.f}, bb = {0.f, 0.f, 0.f, 0.f};
;                 if (NORM) { gg = *(const f32x4*)(gam + col); bb = *(const f32x4*)(bet + col); }
; #pragma unroll
;                 for (int ai = 0; ai < 2; ++ai) {
;                     f32x4 xv[4]; f32x2 st[4];
; #pragma unroll
;                     for (int m = 0; m < 4; ++m) { xv[m] = *(const f32x4*)(X + (size_t)(row0 + ai * HALF + m * 16) * D + col);
;                         if (NORM) st[m] = *(const f32x2*)(stats + 2 * (row0 + ai * HALF + m * 16)); }
; #pragma unroll
;                     for (int m = 0; m < 4; ++m) {
;                         f32x4 x = xv[m];
;                         if (NORM) x = (x - st[m].x) * st[m].y * gg + bb;
;                         if (!dry) *(f32x4*)(X + (size_t)(row0 + ai * HALF + m * 16) * D + col) = x * ALPHA + acc[ai][bj][m][n];
.LBB0_185:
	v_lshl_add_u32 v225, s31, 8, v171
	v_lshl_or_b32 v226, s30, 8, v205
	v_lshlrev_b32_e32 v227, 3, v225
	v_lshlrev_b32_e32 v234, 2, v226
	v_lshl_add_u32 v224, v225, 13, v234
	global_load_dwordx2 v[162:163], v227, s[38:39]
	global_load_dwordx2 v[182:183], v227, s[38:39] offset:128
	global_load_dwordx2 v[184:185], v227, s[38:39] offset:256
	global_load_dwordx2 v[186:187], v227, s[38:39] offset:384
	global_load_dwordx2 v[188:189], v227, s[38:39] offset:1024
	global_load_dwordx2 v[190:191], v227, s[38:39] offset:1152
	global_load_dwordx2 v[192:193], v227, s[38:39] offset:1280
	global_load_dwordx2 v[194:195], v227, s[38:39] offset:1408
	global_load_dwordx4 v[196:199], v234, s[42:43]
	global_load_dwordx4 v[200:203], v234, s[10:11]
	global_load_dwordx4 v[210:213], v234, s[42:43] offset:64
	global_load_dwordx4 v[220:223], v234, s[10:11] offset:64
	global_load_dwordx4 v[138:141], v224, s[14:15]
	v_add_u32_e32 v226, 0x20000, v224
	global_load_dwordx4 v[142:145], v226, s[14:15]
	v_add_u32_e32 v225, 0x40000, v224
	global_load_dwordx4 v[146:149], v225, s[14:15]
	v_add_u32_e32 v226, 0x60000, v224
	global_load_dwordx4 v[150:153], v226, s[14:15]
	v_add_u32_e32 v225, 0x100000, v224
	global_load_dwordx4 v[154:157], v225, s[14:15]
	v_add_u32_e32 v226, 0x120000, v224
	global_load_dwordx4 v[158:161], v226, s[14:15]
	v_add_u32_e32 v225, 0x140000, v224
	global_load_dwordx4 v[174:177], v225, s[14:15]
	v_add_u32_e32 v226, 0x160000, v224
	global_load_dwordx4 v[178:181], v226, s[14:15]
	s_waitcnt vmcnt(4)
	v_pk_add_f32 v[138:139], v[138:139], v[162:163] op_sel_hi:[1,0] neg_lo:[0,1] neg_hi:[0,1]
	v_pk_add_f32 v[140:141], v[140:141], v[162:163] op_sel_hi:[1,0] neg_lo:[0,1] neg_hi:[0,1]
	v_pk_mul_f32 v[140:141], v[162:163], v[140:141] op_sel:[1,0]
	v_pk_mul_f32 v[138:139], v[162:163], v[138:139] op_sel:[1,0]
	v_pk_fma_f32 v[138:139], v[196:197], v[138:139], v[200:201]
	v_pk_fma_f32 v[140:141], v[198:199], v[140:141], v[202:203]
	v_pk_fma_f32 v[130:131], v[140:141], s[34:35], v[130:131] op_sel_hi:[1,0,1]
	v_pk_fma_f32 v[128:129], v[138:139], s[34:35], v[128:129] op_sel_hi:[1,0,1]
	v_pk_add_f32 v[142:143], v[142:143], v[182:183] op_sel_hi:[1,0] neg_lo:[0,1] neg_hi:[0,1]
	v_pk_add_f32 v[144:145], v[144:145], v[182:183] op_sel_hi:[1,0] neg_lo:[0,1] neg_hi:[0,1]
	v_pk_mul_f32 v[144:145], v[182:183], v[144:145] op_sel:[1,0]
	v_pk_mul_f32 v[142:143], v[182:183], v[142:143] op_sel:[1,0]
	v_pk_fma_f32 v[142:143], v[196:197], v[142:143], v[200:201]
	v_pk_fma_f32 v[144:145], v[198:199], v[144:145], v[202:203]
	v_pk_fma_f32 v[126:127], v[144:145], s[34:35], v[126:127] op_sel_hi:[1,0,1]
	v_pk_fma_f32 v[124:125], v[142:143], s[34:35], v[124:125] op_sel_hi:[1,0,1]
	v_pk_add_f32 v[146:147], v[146:147], v[184:185] op_sel_hi:[1,0] neg_lo:[0,1] neg_hi:[0,1]
	v_pk_add_f32 v[148:149], v[148:149], v[184:185] op_sel_hi:[1,0] neg_lo:[0,1] neg_hi:[0,1]
	v_pk_mul_f32 v[148:149], v[184:185], v[148:149] op_sel:[1,0]
	v_pk_mul_f32 v[146:147], v[184:185], v[146:147] op_sel:[1,0]
	v_pk_fma_f32 v[146:147], v[196:197], v[146:147], v[200:201]
	v_pk_fma_f32 v[148:149], v[198:199], v[148:149], v[202:203]
	v_pk_fma_f32 v[122:123], v[148:149], s[34:35], v[122:123] op_sel_hi:[1,0,1]
	v_pk_fma_f32 v[120:121], v[146:147], s[34:35], v[120:121] op_sel_hi:[1,0,1]
	v_pk_add_f32 v[150:151], v[150:151], v[186:187] op_sel_hi:[1,0] neg_lo:[0,1] neg_hi:[0,1]
	v_pk_add_f32 v[152:153], v[152:153], v[186:187] op_sel_hi:[1,0] neg_lo:[0,1] neg_hi:[0,1]
	v_pk_mul_f32 v[152:153], v[186:187], v[152:153] op_sel:[1,0]
	v_pk_mul_f32 v[150:151], v[186:187], v[150:151] op_sel:[1,0]
	v_pk_fma_f32 v[150:151], v[196:197], v[150:151], v[200:201]
	v_pk_fma_f32 v[152:153], v[198:199], v[152:153], v[202:203]
	v_pk_fma_f32 v[118:119], v[152:153], s[34:35], v[118:119] op_sel_hi:[1,0,1]
	v_pk_fma_f32 v[116:117], v[150:151], s[34:35], v[116:117] op_sel_hi:[1,0,1]
	global_load_dwordx4 v[138:141], v224, s[14:15] offset:64
	v_add_u32_e32 v226, 0x20000, v224
	global_load_dwordx4 v[142:145], v226, s[14:15] offset:64
	v_add_u32_e32 v225, 0x40000, v224
	global_load_dwordx4 v[146:149], v225, s[14:15] offset:64
	v_add_u32_e32 v226, 0x60000, v224
	global_load_dwordx4 v[150:153], v226, s[14:15] offset:64
	global_store_dwordx4 v224, v[128:131], s[14:15]
	v_add_u32_e32 v226, 0x20000, v224
	global_store_dwordx4 v226, v[124:127], s[14:15]
	v_add_u32_e32 v225, 0x40000, v224
	global_store_dwordx4 v225, v[120:123], s[14:15]
	v_add_u32_e32 v226, 0x60000, v224
	global_store_dwordx4 v226, v[116:119], s[14:15]
	s_waitcnt vmcnt(8)
;     __device__ __forceinline__ void operator()(const f32x4 (&acc)[2][2][4][2], const Unit& u, int wr, int wc, int fr, int fq) const {
;     ...
;             for (int n = 0; n < 2; ++n) {
;                 const int col = col0 + bj * HALF + n * 16;
;                 f32x4 gg = {1.f, 1.f, 1.f, 1.f}, bb = {0.f, 0.f, 0.f, 0.f};
;                 if (NORM) { gg = *(const f32x4*)(gam + col); bb = *(const f32x4*)(bet + col); }
; #pragma unroll
;                 for (int ai = 0; ai < 2; ++ai) {
;                     f32x4 xv[4]; f32x2 st[4];
; #pragma unroll
;                     for (int m = 0; m < 4; ++m) { xv[m] = *(const f32x4*)(X + (size_t)(row0 + ai * HALF + m * 16) * D + col);
;                         if (NORM) st[m] = *(const f32x2*)(stats + 2 * (row0 + ai * HALF + m * 16)); }
; #pragma unroll
;                     for (int m = 0; m < 4; ++m) {
;                         f32x4 x = xv[m];
;                         if (NORM) x = (x - st[m].x) * st[m].y * gg + bb;
;                         if (!dry) *(f32x4*)(X + (size_t)(row0 + ai * HALF + m * 16) * D + col) = x * ALPHA + acc[ai][bj][m][n];
;                     }
	v_pk_add_f32 v[154:155], v[154:155], v[188:189] op_sel_hi:[1,0] neg_lo:[0,1] neg_hi:[0,1]
	v_pk_add_f32 v[156:157], v[156:157], v[188:189] op_sel_hi:[1,0] neg_lo:[0,1] neg_hi:[0,1]
	v_pk_mul_f32 v[156:157], v[188:189], v[156:157] op_sel:[1,0]
	v_pk_mul_f32 v[154:155], v[188:189], v[154:155] op_sel:[1,0]
	v_pk_fma_f32 v[154:155], v[196:197], v[154:155], v[200:201]
	v_pk_fma_f32 v[156:157], v[198:199], v[156:157], v[202:203]
	v_pk_fma_f32 v[114:115], v[156:157], s[34:35], v[114:115] op_sel_hi:[1,0,1]
	v_pk_fma_f32 v[112:113], v[154:155], s[34:35], v[112:113] op_sel_hi:[1,0,1]
	v_pk_add_f32 v[158:159], v[158:159], v[190:191] op_sel_hi:[1,0] neg_lo:[0,1] neg_hi:[0,1]
	v_pk_add_f32 v[160:161], v[160:161], v[190:191] op_sel_hi:[1,0] neg_lo:[0,1] neg_hi:[0,1]
	v_pk_mul_f32 v[160:161], v[190:191], v[160:161] op_sel:[1,0]
	v_pk_mul_f32 v[158:159], v[190:191], v[158:159] op_sel:[1,0]
	v_pk_fma_f32 v[158:159], v[196:197], v[158:159], v[200:201]
	v_pk_fma_f32 v[160:161], v[198:199], v[160:161], v[202:203]
	v_pk_fma_f32 v[110:111], v[160:161], s[34:35], v[110:111] op_sel_hi:[1,0,1]
	v_pk_fma_f32 v[108:109], v[158:159], s[34:35], v[108:109] op_sel_hi:[1,0,1]
	v_pk_add_f32 v[174:175], v[174:175], v[192:193] op_sel_hi:[1,0] neg_lo:[0,1] neg_hi:[0,1]
	v_pk_add_f32 v[176:177], v[176:177], v[192:193] op_sel_hi:[1,0] neg_lo:[0,1] neg_hi:[0,1]
	v_pk_mul_f32 v[176:177], v[192:193], v[176:177] op_sel:[1,0]
	v_pk_mul_f32 v[174:175], v[192:193], v[174:175] op_sel:[1,0]
	v_pk_fma_f32 v[174:175], v[196:197], v[174:175], v[200:201]
	v_pk_fma_f32 v[176:177], v[198:199], v[176:177], v[202:203]
	v_pk_fma_f32 v[106:107], v[176:177], s[34:35], v[106:107] op_sel_hi:[1,0,1]
	v_pk_fma_f32 v[104:105], v[174:175], s[34:35], v[104:105] op_sel_hi:[1,0,1]
	v_pk_add_f32 v[178:179], v[178:179], v[194:195] op_sel_hi:[1,0] neg_lo:[0,1] neg_hi:[0,1]
	v_pk_add_f32 v[180:181], v[180:181], v[194:195] op_sel_hi:[1,0] neg_lo:[0,1] neg_hi:[0,1]
	v_pk_mul_f32 v[180:181], v[194:195], v[180:181] op_sel:[1,0]
	v_pk_mul_f32 v[178:179], v[194:195], v[178:179] op_sel:[1,0]
	v_pk_fma_f32 v[178:179], v[196:197], v[178:179], v[200:201]
	v_pk_fma_f32 v[180:181], v[198:199], v[180:181], v[202:203]
	v_pk_fma_f32 v[102:103], v[180:181], s[34:35], v[102:103] op_sel_hi:[1,0,1]
	v_pk_fma_f32 v[100:101], v[178:179], s[34:35], v[100:101] op_sel_hi:[1,0,1]
	global_load_dwordx4 v[196:199], v234, s[42:43] offset:512
	global_load_dwordx4 v[200:203], v234, s[10:11] offset:512
	v_add_u32_e32 v225, 0x100000, v224
	global_load_dwordx4 v[154:157], v225, s[14:15] offset:64
	v_add_u32_e32 v226, 0x120000, v224
	global_load_dwordx4 v[158:161], v226, s[14:15] offset:64
	v_add_u32_e32 v225, 0x140000, v224
	global_load_dwordx4 v[174:177], v225, s[14:15] offset:64
	v_add_u32_e32 v226, 0x160000, v224
	global_load_dwordx4 v[178:181], v226, s[14:15] offset:64
	v_add_u32_e32 v225, 0x100000, v224
	global_store_dwordx4 v225, v[112:115], s[14:15]
	v_add_u32_e32 v226, 0x120000, v224
	global_store_dwordx4 v226, v[108:111], s[14:15]
	v_add_u32_e32 v225, 0x140000, v224
	global_store_dwordx4 v225, v[104:107], s[14:15]
	v_add_u32_e32 v226, 0x160000, v224
	global_store_dwordx4 v226, v[100:103], s[14:15]
	s_waitcnt vmcnt(14)
	v_pk_add_f32 v[138:139], v[138:139], v[162:163] op_sel_hi:[1,0] neg_lo:[0,1] neg_hi:[0,1]
	v_pk_add_f32 v[140:141], v[140:141], v[162:163] op_sel_hi:[1,0] neg_lo:[0,1] neg_hi:[0,1]
	v_pk_mul_f32 v[140:141], v[162:163], v[140:141] op_sel:[1,0]
	v_pk_mul_f32 v[138:139], v[162:163], v[138:139] op_sel:[1,0]
	v_pk_fma_f32 v[138:139], v[210:211], v[138:139], v[220:221]
	v_pk_fma_f32 v[140:141], v[212:213], v[140:141], v[222:223]
	v_pk_fma_f32 v[98:99], v[140:141], s[34:35], v[98:99] op_sel_hi:[1,0,1]
	v_pk_fma_f32 v[96:97], v[138:139], s[34:35], v[96:97] op_sel_hi:[1,0,1]
	v_pk_add_f32 v[142:143], v[142:143], v[182:183] op_sel_hi:[1,0] neg_lo:[0,1] neg_hi:[0,1]
	v_pk_add_f32 v[144:145], v[144:145], v[182:183] op_sel_hi:[1,0] neg_lo:[0,1] neg_hi:[0,1]
	v_pk_mul_f32 v[144:145], v[182:183], v[144:145] op_sel:[1,0]
	v_pk_mul_f32 v[142:143], v[182:183], v[142:143] op_sel:[1,0]
	v_pk_fma_f32 v[142:143], v[210:211], v[142:143], v[220:221]
	v_pk_fma_f32 v[144:145], v[212:213], v[144:145], v[222:223]
	v_pk_fma_f32 v[94:95], v[144:145], s[34:35], v[94:95] op_sel_hi:[1,0,1]
	v_pk_fma_f32 v[92:93], v[142:143], s[34:35], v[92:93] op_sel_hi:[1,0,1]
	v_pk_add_f32 v[146:147], v[146:147], v[184:185] op_sel_hi:[1,0] neg_lo:[0,1] neg_hi:[0,1]
	v_pk_add_f32 v[148:149], v[148:149], v[184:185] op_sel_hi:[1,0] neg_lo:[0,1] neg_hi:[0,1]
	v_pk_mul_f32 v[148:149], v[184:185], v[148:149] op_sel:[1,0]
	v_pk_mul_f32 v[146:147], v[184:185], v[146:147] op_sel:[1,0]
	v_pk_fma_f32 v[146:147], v[210:211], v[146:147], v[220:221]
	v_pk_fma_f32 v[148:149], v[212:213], v[148:149], v[222:223]
	v_pk_fma_f32 v[90:91], v[148:149], s[34:35], v[90:91] op_sel_hi:[1,0,1]
	v_pk_fma_f32 v[88:89], v[146:147], s[34:35], v[88:89] op_sel_hi:[1,0,1]
	v_pk_add_f32 v[150:151], v[150:151], v[186:187] op_sel_hi:[1,0] neg_lo:[0,1] neg_hi:[0,1]
	v_pk_add_f32 v[152:153], v[152:153], v[186:187] op_sel_hi:[1,0] neg_lo:[0,1] neg_hi:[0,1]
	v_pk_mul_f32 v[152:153], v[186:187], v[152:153] op_sel:[1,0]
	v_pk_mul_f32 v[150:151], v[186:187], v[150:151] op_sel:[1,0]
	v_pk_fma_f32 v[150:151], v[210:211], v[150:151], v[220:221]
	v_pk_fma_f32 v[152:153], v[212:213], v[152:153], v[222:223]
	v_pk_fma_f32 v[86:87], v[152:153], s[34:35], v[86:87] op_sel_hi:[1,0,1]
	v_pk_fma_f32 v[84:85], v[150:151], s[34:35], v[84:85] op_sel_hi:[1,0,1]
	global_load_dwordx4 v[138:141], v224, s[14:15] offset:512
	v_add_u32_e32 v226, 0x20000, v224
	global_load_dwordx4 v[142:145], v226, s[14:15] offset:512
	v_add_u32_e32 v225, 0x40000, v224
	global_load_dwordx4 v[146:149], v225, s[14:15] offset:512
	v_add_u32_e32 v226, 0x60000, v224
	global_load_dwordx4 v[150:153], v226, s[14:15] offset:512
	global_store_dwordx4 v224, v[96:99], s[14:15] offset:64
	v_add_u32_e32 v226, 0x20000, v224
	global_store_dwordx4 v226, v[92:95], s[14:15] offset:64
	v_add_u32_e32 v225, 0x40000, v224
	global_store_dwordx4 v225, v[88:91], s[14:15] offset:64
	v_add_u32_e32 v226, 0x60000, v224
	global_store_dwordx4 v226, v[84:87], s[14:15] offset:64
	s_waitcnt vmcnt(12)
;     __device__ __forceinline__ void operator()(const f32x4 (&acc)[2][2][4][2], const Unit& u, int wr, int wc, int fr, int fq) const {
;     ...
;             for (int n = 0; n < 2; ++n) {
;                 const int col = col0 + bj * HALF + n * 16;
;                 f32x4 gg = {1.f, 1.f, 1.f, 1.f}, bb = {0.f, 0.f, 0.f, 0.f};
;                 if (NORM) { gg = *(const f32x4*)(gam + col); bb = *(const f32x4*)(bet + col); }
; #pragma unroll
;                 for (int ai = 0; ai < 2; ++ai) {
;                     f32x4 xv[4]; f32x2 st[4];
; #pragma unroll
;                     for (int m = 0; m < 4; ++m) { xv[m] = *(const f32x4*)(X + (size_t)(row0 + ai * HALF + m * 16) * D + col);
;                         if (NORM) st[m] = *(const f32x2*)(stats + 2 * (row0 + ai * HALF + m * 16)); }
; #pragma unroll
;                     for (int m = 0; m < 4; ++m) {
;                         f32x4 x = xv[m];
;                         if (NORM) x = (x - st[m].x) * st[m].y * gg + bb;
;                         if (!dry) *(f32x4*)(X + (size_t)(row0 + ai * HALF + m * 16) * D + col) = x * ALPHA + acc[ai][bj][m][n];
;                     }
	v_pk_add_f32 v[154:155], v[154:155], v[188:189] op_sel_hi:[1,0] neg_lo:[0,1] neg_hi:[0,1]
	v_pk_add_f32 v[156:157], v[156:157], v[188:189] op_sel_hi:[1,0] neg_lo:[0,1] neg_hi:[0,1]
	v_pk_mul_f32 v[156:157], v[188:189], v[156:157] op_sel:[1,0]
	v_pk_mul_f32 v[154:155], v[188:189], v[154:155] op_sel:[1,0]
	v_pk_fma_f32 v[154:155], v[210:211], v[154:155], v[220:221]
	v_pk_fma_f32 v[156:157], v[212:213], v[156:157], v[222:223]
	v_pk_fma_f32 v[82:83], v[156:157], s[34:35], v[82:83] op_sel_hi:[1,0,1]
	v_pk_fma_f32 v[80:81], v[154:155], s[34:35], v[80:81] op_sel_hi:[1,0,1]
	v_pk_add_f32 v[158:159], v[158:159], v[190:191] op_sel_hi:[1,0] neg_lo:[0,1] neg_hi:[0,1]
	v_pk_add_f32 v[160:161], v[160:161], v[190:191] op_sel_hi:[1,0] neg_lo:[0,1] neg_hi:[0,1]
	v_pk_mul_f32 v[160:161], v[190:191], v[160:161] op_sel:[1,0]
	v_pk_mul_f32 v[158:159], v[190:191], v[158:159] op_sel:[1,0]
	v_pk_fma_f32 v[158:159], v[210:211], v[158:159], v[220:221]
	v_pk_fma_f32 v[160:161], v[212:213], v[160:161], v[222:223]
	v_pk_fma_f32 v[78:79], v[160:161], s[34:35], v[78:79] op_sel_hi:[1,0,1]
	v_pk_fma_f32 v[76:77], v[158:159], s[34:35], v[76:77] op_sel_hi:[1,0,1]
	v_pk_add_f32 v[174:175], v[174:175], v[192:193] op_sel_hi:[1,0] neg_lo:[0,1] neg_hi:[0,1]
	v_pk_add_f32 v[176:177], v[176:177], v[192:193] op_sel_hi:[1,0] neg_lo:[0,1] neg_hi:[0,1]
	v_pk_mul_f32 v[176:177], v[192:193], v[176:177] op_sel:[1,0]
	v_pk_mul_f32 v[174:175], v[192:193], v[174:175] op_sel:[1,0]
	v_pk_fma_f32 v[174:175], v[210:211], v[174:175], v[220:221]
	v_pk_fma_f32 v[176:177], v[212:213], v[176:177], v[222:223]
	v_pk_fma_f32 v[74:75], v[176:177], s[34:35], v[74:75] op_sel_hi:[1,0,1]
	v_pk_fma_f32 v[72:73], v[174:175], s[34:35], v[72:73] op_sel_hi:[1,0,1]
	v_pk_add_f32 v[178:179], v[178:179], v[194:195] op_sel_hi:[1,0] neg_lo:[0,1] neg_hi:[0,1]
	v_pk_add_f32 v[180:181], v[180:181], v[194:195] op_sel_hi:[1,0] neg_lo:[0,1] neg_hi:[0,1]
	v_pk_mul_f32 v[180:181], v[194:195], v[180:181] op_sel:[1,0]
	v_pk_mul_f32 v[178:179], v[194:195], v[178:179] op_sel:[1,0]
	v_pk_fma_f32 v[178:179], v[210:211], v[178:179], v[220:221]
	v_pk_fma_f32 v[180:181], v[212:213], v[180:181], v[222:223]
	v_pk_fma_f32 v[70:71], v[180:181], s[34:35], v[70:71] op_sel_hi:[1,0,1]
	v_pk_fma_f32 v[68:69], v[178:179], s[34:35], v[68:69] op_sel_hi:[1,0,1]
	global_load_dwordx4 v[210:213], v234, s[42:43] offset:576
	global_load_dwordx4 v[220:223], v234, s[10:11] offset:576
	v_add_u32_e32 v225, 0x100000, v224
	global_load_dwordx4 v[154:157], v225, s[14:15] offset:512
	v_add_u32_e32 v226, 0x120000, v224
	global_load_dwordx4 v[158:161], v226, s[14:15] offset:512
	v_add_u32_e32 v225, 0x140000, v224
	global_load_dwordx4 v[174:177], v225, s[14:15] offset:512
	v_add_u32_e32 v226, 0x160000, v224
	global_load_dwordx4 v[178:181], v226, s[14:15] offset:512
	v_add_u32_e32 v225, 0x100000, v224
	global_store_dwordx4 v225, v[80:83], s[14:15] offset:64
	v_add_u32_e32 v226, 0x120000, v224
	global_store_dwordx4 v226, v[76:79], s[14:15] offset:64
	v_add_u32_e32 v225, 0x140000, v224
	global_store_dwordx4 v225, v[72:75], s[14:15] offset:64
	v_add_u32_e32 v226, 0x160000, v224
	global_store_dwordx4 v226, v[68:71], s[14:15] offset:64
	s_waitcnt vmcnt(14)
	v_pk_add_f32 v[138:139], v[138:139], v[162:163] op_sel_hi:[1,0] neg_lo:[0,1] neg_hi:[0,1]
	v_pk_add_f32 v[140:141], v[140:141], v[162:163] op_sel_hi:[1,0] neg_lo:[0,1] neg_hi:[0,1]
	v_pk_mul_f32 v[140:141], v[162:163], v[140:141] op_sel:[1,0]
	v_pk_mul_f32 v[138:139], v[162:163], v[138:139] op_sel:[1,0]
	v_pk_fma_f32 v[138:139], v[196:197], v[138:139], v[200:201]
	v_pk_fma_f32 v[140:141], v[198:199], v[140:141], v[202:203]
	v_pk_fma_f32 v[66:67], v[140:141], s[34:35], v[66:67] op_sel_hi:[1,0,1]
	v_pk_fma_f32 v[64:65], v[138:139], s[34:35], v[64:65] op_sel_hi:[1,0,1]
	v_pk_add_f32 v[142:143], v[142:143], v[182:183] op_sel_hi:[1,0] neg_lo:[0,1] neg_hi:[0,1]
	v_pk_add_f32 v[144:145], v[144:145], v[182:183] op_sel_hi:[1,0] neg_lo:[0,1] neg_hi:[0,1]
	v_pk_mul_f32 v[144:145], v[182:183], v[144:145] op_sel:[1,0]
	v_pk_mul_f32 v[142:143], v[182:183], v[142:143] op_sel:[1,0]
	v_pk_fma_f32 v[142:143], v[196:197], v[142:143], v[200:201]
	v_pk_fma_f32 v[144:145], v[198:199], v[144:145], v[202:203]
	v_pk_fma_f32 v[62:63], v[144:145], s[34:35], v[62:63] op_sel_hi:[1,0,1]
	v_pk_fma_f32 v[60:61], v[142:143], s[34:35], v[60:61] op_sel_hi:[1,0,1]
	v_pk_add_f32 v[146:147], v[146:147], v[184:185] op_sel_hi:[1,0] neg_lo:[0,1] neg_hi:[0,1]
	v_pk_add_f32 v[148:149], v[148:149], v[184:185] op_sel_hi:[1,0] neg_lo:[0,1] neg_hi:[0,1]
	v_pk_mul_f32 v[148:149], v[184:185], v[148:149] op_sel:[1,0]
	v_pk_mul_f32 v[146:147], v[184:185], v[146:147] op_sel:[1,0]
	v_pk_fma_f32 v[146:147], v[196:197], v[146:147], v[200:201]
	v_pk_fma_f32 v[148:149], v[198:199], v[148:149], v[202:203]
	v_pk_fma_f32 v[58:59], v[148:149], s[34:35], v[58:59] op_sel_hi:[1,0,1]
	v_pk_fma_f32 v[56:57], v[146:147], s[34:35], v[56:57] op_sel_hi:[1,0,1]
	v_pk_add_f32 v[150:151], v[150:151], v[186:187] op_sel_hi:[1,0] neg_lo:[0,1] neg_hi:[0,1]
	v_pk_add_f32 v[152:153], v[152:153], v[186:187] op_sel_hi:[1,0] neg_lo:[0,1] neg_hi:[0,1]
	v_pk_mul_f32 v[152:153], v[186:187], v[152:153] op_sel:[1,0]
	v_pk_mul_f32 v[150:151], v[186:187], v[150:151] op_sel:[1,0]
	v_pk_fma_f32 v[150:151], v[196:197], v[150:151], v[200:201]
	v_pk_fma_f32 v[152:153], v[198:199], v[152:153], v[202:203]
	v_pk_fma_f32 v[54:55], v[152:153], s[34:35], v[54:55] op_sel_hi:[1,0,1]
	v_pk_fma_f32 v[52:53], v[150:151], s[34:35], v[52:53] op_sel_hi:[1,0,1]
	global_load_dwordx4 v[138:141], v224, s[14:15] offset:576
	v_add_u32_e32 v226, 0x20000, v224
	global_load_dwordx4 v[142:145], v226, s[14:15] offset:576
	v_add_u32_e32 v225, 0x40000, v224
	global_load_dwordx4 v[146:149], v225, s[14:15] offset:576
	v_add_u32_e32 v226, 0x60000, v224
	global_load_dwordx4 v[150:153], v226, s[14:15] offset:576
	global_store_dwordx4 v224, v[64:67], s[14:15] offset:512
	v_add_u32_e32 v226, 0x20000, v224
	global_store_dwordx4 v226, v[60:63], s[14:15] offset:512
	v_add_u32_e32 v225, 0x40000, v224
	global_store_dwordx4 v225, v[56:59], s[14:15] offset:512
	v_add_u32_e32 v226, 0x60000, v224
	global_store_dwordx4 v226, v[52:55], s[14:15] offset:512
	s_waitcnt vmcnt(12)
;     __device__ __forceinline__ void operator()(const f32x4 (&acc)[2][2][4][2], const Unit& u, int wr, int wc, int fr, int fq) const {
;     ...
;             for (int n = 0; n < 2; ++n) {
;                 const int col = col0 + bj * HALF + n * 16;
;                 f32x4 gg = {1.f, 1.f, 1.f, 1.f}, bb = {0.f, 0.f, 0.f, 0.f};
;                 if (NORM) { gg = *(const f32x4*)(gam + col); bb = *(const f32x4*)(bet + col); }
; #pragma unroll
;                 for (int ai = 0; ai < 2; ++ai) {
;                     f32x4 xv[4]; f32x2 st[4];
; #pragma unroll
;                     for (int m = 0; m < 4; ++m) { xv[m] = *(const f32x4*)(X + (size_t)(row0 + ai * HALF + m * 16) * D + col);
;                         if (NORM) st[m] = *(const f32x2*)(stats + 2 * (row0 + ai * HALF + m * 16)); }
; #pragma unroll
;                     for (int m = 0; m < 4; ++m) {
;                         f32x4 x = xv[m];
;                         if (NORM) x = (x - st[m].x) * st[m].y * gg + bb;
;                         if (!dry) *(f32x4*)(X + (size_t)(row0 + ai * HALF + m * 16) * D + col) = x * ALPHA + acc[ai][bj][m][n];
;                     }
	v_pk_add_f32 v[154:155], v[154:155], v[188:189] op_sel_hi:[1,0] neg_lo:[0,1] neg_hi:[0,1]
	v_pk_add_f32 v[156:157], v[156:157], v[188:189] op_sel_hi:[1,0] neg_lo:[0,1] neg_hi:[0,1]
	v_pk_mul_f32 v[156:157], v[188:189], v[156:157] op_sel:[1,0]
	v_pk_mul_f32 v[154:155], v[188:189], v[154:155] op_sel:[1,0]
	v_pk_fma_f32 v[154:155], v[196:197], v[154:155], v[200:201]
	v_pk_fma_f32 v[156:157], v[198:199], v[156:157], v[202:203]
	v_pk_fma_f32 v[50:51], v[156:157], s[34:35], v[50:51] op_sel_hi:[1,0,1]
	v_pk_fma_f32 v[48:49], v[154:155], s[34:35], v[48:49] op_sel_hi:[1,0,1]
	v_pk_add_f32 v[158:159], v[158:159], v[190:191] op_sel_hi:[1,0] neg_lo:[0,1] neg_hi:[0,1]
	v_pk_add_f32 v[160:161], v[160:161], v[190:191] op_sel_hi:[1,0] neg_lo:[0,1] neg_hi:[0,1]
	v_pk_mul_f32 v[160:161], v[190:191], v[160:161] op_sel:[1,0]
	v_pk_mul_f32 v[158:159], v[190:191], v[158:159] op_sel:[1,0]
	v_pk_fma_f32 v[158:159], v[196:197], v[158:159], v[200:201]
	v_pk_fma_f32 v[160:161], v[198:199], v[160:161], v[202:203]
	v_pk_fma_f32 v[46:47], v[160:161], s[34:35], v[46:47] op_sel_hi:[1,0,1]
	v_pk_fma_f32 v[44:45], v[158:159], s[34:35], v[44:45] op_sel_hi:[1,0,1]
	v_pk_add_f32 v[174:175], v[174:175], v[192:193] op_sel_hi:[1,0] neg_lo:[0,1] neg_hi:[0,1]
	v_pk_add_f32 v[176:177], v[176:177], v[192:193] op_sel_hi:[1,0] neg_lo:[0,1] neg_hi:[0,1]
	v_pk_mul_f32 v[176:177], v[192:193], v[176:177] op_sel:[1,0]
	v_pk_mul_f32 v[174:175], v[192:193], v[174:175] op_sel:[1,0]
	v_pk_fma_f32 v[174:175], v[196:197], v[174:175], v[200:201]
	v_pk_fma_f32 v[176:177], v[198:199], v[176:177], v[202:203]
	v_pk_fma_f32 v[42:43], v[176:177], s[34:35], v[42:43] op_sel_hi:[1,0,1]
	v_pk_fma_f32 v[40:41], v[174:175], s[34:35], v[40:41] op_sel_hi:[1,0,1]
	v_pk_add_f32 v[178:179], v[178:179], v[194:195] op_sel_hi:[1,0] neg_lo:[0,1] neg_hi:[0,1]
	v_pk_add_f32 v[180:181], v[180:181], v[194:195] op_sel_hi:[1,0] neg_lo:[0,1] neg_hi:[0,1]
	v_pk_mul_f32 v[180:181], v[194:195], v[180:181] op_sel:[1,0]
	v_pk_mul_f32 v[178:179], v[194:195], v[178:179] op_sel:[1,0]
	v_pk_fma_f32 v[178:179], v[196:197], v[178:179], v[200:201]
	v_pk_fma_f32 v[180:181], v[198:199], v[180:181], v[202:203]
	v_pk_fma_f32 v[38:39], v[180:181], s[34:35], v[38:39] op_sel_hi:[1,0,1]
	v_pk_fma_f32 v[36:37], v[178:179], s[34:35], v[36:37] op_sel_hi:[1,0,1]
	v_add_u32_e32 v225, 0x100000, v224
	global_load_dwordx4 v[154:157], v225, s[14:15] offset:576
	v_add_u32_e32 v226, 0x120000, v224
	global_load_dwordx4 v[158:161], v226, s[14:15] offset:576
	v_add_u32_e32 v225, 0x140000, v224
	global_load_dwordx4 v[174:177], v225, s[14:15] offset:576
	v_add_u32_e32 v226, 0x160000, v224
	global_load_dwordx4 v[178:181], v226, s[14:15] offset:576
	v_add_u32_e32 v225, 0x100000, v224
	global_store_dwordx4 v225, v[48:51], s[14:15] offset:512
	v_add_u32_e32 v226, 0x120000, v224
	global_store_dwordx4 v226, v[44:47], s[14:15] offset:512
	v_add_u32_e32 v225, 0x140000, v224
	global_store_dwordx4 v225, v[40:43], s[14:15] offset:512
	v_add_u32_e32 v226, 0x160000, v224
	global_store_dwordx4 v226, v[36:39], s[14:15] offset:512
	s_waitcnt vmcnt(12)
; #define PG8_BAR __builtin_amdgcn_s_barrier()
; template <class Epi, class Sched>
; __device__ __forceinline__ void gemm_phase(LAS unsigned char* lds, const Gemm g, const Sched& S, const Epi& E, const int tid) {
;     ...
;         if (wr == 0) PG8_BAR;
;         E(acc, cur, wr, wc, fr, fq);
;         if (!has_next) break;
; #pragma unroll
;         for (int a = 0; a < 2; ++a)
; #pragma unroll
;             for (int b = 0; b < 2; ++b)
; #pragma unroll
;                 for (int m = 0; m < 4; ++m)
; #pragma unroll
;                     for (int n = 0; n < 2; ++n) acc[a][b][m][n] = (f32x4){0.f, 0.f, 0.f, 0.f};
;         cur = nxt; cA = nA; cB = nB; ++ui;
;         if (wr == 1) PG8_BAR;
;     __device__ __forceinline__ void operator()(const f32x4 (&acc)[2][2][4][2], const Unit& u, int wr, int wc, int fr, int fq) const {
;     ...
;             for (int n = 0; n < 2; ++n) {
;                 const int col = col0 + bj * HALF + n * 16;
;                 f32x4 gg = {1.f, 1.f, 1.f, 1.f}, bb = {0.f, 0.f, 0.f, 0.f};
;                 if (NORM) { gg = *(const f32x4*)(gam + col); bb = *(const f32x4*)(bet + col); }
; #pragma unroll
;                 for (int ai = 0; ai < 2; ++ai) {
;                     f32x4 xv[4]; f32x2 st[4];
; #pragma unroll
;                     for (int m = 0; m < 4; ++m) { xv[m] = *(const f32x4*)(X + (size_t)(row0 + ai * HALF + m * 16) * D + col);
;                         if (NORM) st[m] = *(const f32x2*)(stats + 2 * (row0 + ai * HALF + m * 16)); }
; #pragma unroll
;                     for (int m = 0; m < 4; ++m) {
;                         f32x4 x = xv[m];
;                         if (NORM) x = (x - st[m].x) * st[m].y * gg + bb;
;                         if (!dry) *(f32x4*)(X + (size_t)(row0 + ai * HALF + m * 16) * D + col) = x * ALPHA + acc[ai][bj][m][n];
;                     }
	v_pk_add_f32 v[138:139], v[138:139], v[162:163] op_sel_hi:[1,0] neg_lo:[0,1] neg_hi:[0,1]
	v_pk_add_f32 v[140:141], v[140:141], v[162:163] op_sel_hi:[1,0] neg_lo:[0,1] neg_hi:[0,1]
	v_pk_mul_f32 v[140:141], v[162:163], v[140:141] op_sel:[1,0]
	v_pk_mul_f32 v[138:139], v[162:163], v[138:139] op_sel:[1,0]
	v_pk_fma_f32 v[138:139], v[210:211], v[138:139], v[220:221]
	v_pk_fma_f32 v[140:141], v[212:213], v[140:141], v[222:223]
	v_pk_fma_f32 v[34:35], v[140:141], s[34:35], v[34:35] op_sel_hi:[1,0,1]
	v_pk_fma_f32 v[32:33], v[138:139], s[34:35], v[32:33] op_sel_hi:[1,0,1]
	v_pk_add_f32 v[142:143], v[142:143], v[182:183] op_sel_hi:[1,0] neg_lo:[0,1] neg_hi:[0,1]
	v_pk_add_f32 v[144:145], v[144:145], v[182:183] op_sel_hi:[1,0] neg_lo:[0,1] neg_hi:[0,1]
	v_pk_mul_f32 v[144:145], v[182:183], v[144:145] op_sel:[1,0]
	v_pk_mul_f32 v[142:143], v[182:183], v[142:143] op_sel:[1,0]
	v_pk_fma_f32 v[142:143], v[210:211], v[142:143], v[220:221]
	v_pk_fma_f32 v[144:145], v[212:213], v[144:145], v[222:223]
	v_pk_fma_f32 v[30:31], v[144:145], s[34:35], v[30:31] op_sel_hi:[1,0,1]
	v_pk_fma_f32 v[28:29], v[142:143], s[34:35], v[28:29] op_sel_hi:[1,0,1]
	v_pk_add_f32 v[146:147], v[146:147], v[184:185] op_sel_hi:[1,0] neg_lo:[0,1] neg_hi:[0,1]
	v_pk_add_f32 v[148:149], v[148:149], v[184:185] op_sel_hi:[1,0] neg_lo:[0,1] neg_hi:[0,1]
	v_pk_mul_f32 v[148:149], v[184:185], v[148:149] op_sel:[1,0]
	v_pk_mul_f32 v[146:147], v[184:185], v[146:147] op_sel:[1,0]
	v_pk_fma_f32 v[146:147], v[210:211], v[146:147], v[220:221]
	v_pk_fma_f32 v[148:149], v[212:213], v[148:149], v[222:223]
	v_pk_fma_f32 v[26:27], v[148:149], s[34:35], v[26:27] op_sel_hi:[1,0,1]
	v_pk_fma_f32 v[24:25], v[146:147], s[34:35], v[24:25] op_sel_hi:[1,0,1]
	v_pk_add_f32 v[150:151], v[150:151], v[186:187] op_sel_hi:[1,0] neg_lo:[0,1] neg_hi:[0,1]
	v_pk_add_f32 v[152:153], v[152:153], v[186:187] op_sel_hi:[1,0] neg_lo:[0,1] neg_hi:[0,1]
	v_pk_mul_f32 v[152:153], v[186:187], v[152:153] op_sel:[1,0]
	v_pk_mul_f32 v[150:151], v[186:187], v[150:151] op_sel:[1,0]
	v_pk_fma_f32 v[150:151], v[210:211], v[150:151], v[220:221]
	v_pk_fma_f32 v[152:153], v[212:213], v[152:153], v[222:223]
	v_pk_fma_f32 v[22:23], v[152:153], s[34:35], v[22:23] op_sel_hi:[1,0,1]
	v_pk_fma_f32 v[20:21], v[150:151], s[34:35], v[20:21] op_sel_hi:[1,0,1]
	global_store_dwordx4 v224, v[32:35], s[14:15] offset:576
	v_add_u32_e32 v226, 0x20000, v224
	global_store_dwordx4 v226, v[28:31], s[14:15] offset:576
	v_add_u32_e32 v225, 0x40000, v224
	global_store_dwordx4 v225, v[24:27], s[14:15] offset:576
	v_add_u32_e32 v226, 0x60000, v224
	global_store_dwordx4 v226, v[20:23], s[14:15] offset:576
	s_waitcnt vmcnt(8)
	v_pk_add_f32 v[154:155], v[154:155], v[188:189] op_sel_hi:[1,0] neg_lo:[0,1] neg_hi:[0,1]
	v_pk_add_f32 v[156:157], v[156:157], v[188:189] op_sel_hi:[1,0] neg_lo:[0,1] neg_hi:[0,1]
	v_pk_mul_f32 v[156:157], v[188:189], v[156:157] op_sel:[1,0]
	v_pk_mul_f32 v[154:155], v[188:189], v[154:155] op_sel:[1,0]
	v_pk_fma_f32 v[154:155], v[210:211], v[154:155], v[220:221]
	v_pk_fma_f32 v[156:157], v[212:213], v[156:157], v[222:223]
	v_pk_fma_f32 v[18:19], v[156:157], s[34:35], v[18:19] op_sel_hi:[1,0,1]
	v_pk_fma_f32 v[16:17], v[154:155], s[34:35], v[16:17] op_sel_hi:[1,0,1]
	v_pk_add_f32 v[158:159], v[158:159], v[190:191] op_sel_hi:[1,0] neg_lo:[0,1] neg_hi:[0,1]
	v_pk_add_f32 v[160:161], v[160:161], v[190:191] op_sel_hi:[1,0] neg_lo:[0,1] neg_hi:[0,1]
	v_pk_mul_f32 v[160:161], v[190:191], v[160:161] op_sel:[1,0]
	v_pk_mul_f32 v[158:159], v[190:191], v[158:159] op_sel:[1,0]
	v_pk_fma_f32 v[158:159], v[210:211], v[158:159], v[220:221]
	v_pk_fma_f32 v[160:161], v[212:213], v[160:161], v[222:223]
	v_pk_fma_f32 v[14:15], v[160:161], s[34:35], v[14:15] op_sel_hi:[1,0,1]
	v_pk_fma_f32 v[12:13], v[158:159], s[34:35], v[12:13] op_sel_hi:[1,0,1]
	v_pk_add_f32 v[174:175], v[174:175], v[192:193] op_sel_hi:[1,0] neg_lo:[0,1] neg_hi:[0,1]
	v_pk_add_f32 v[176:177], v[176:177], v[192:193] op_sel_hi:[1,0] neg_lo:[0,1] neg_hi:[0,1]
	v_pk_mul_f32 v[176:177], v[192:193], v[176:177] op_sel:[1,0]
	v_pk_mul_f32 v[174:175], v[192:193], v[174:175] op_sel:[1,0]
	v_pk_fma_f32 v[174:175], v[210:211], v[174:175], v[220:221]
	v_pk_fma_f32 v[176:177], v[212:213], v[176:177], v[222:223]
	v_pk_fma_f32 v[10:11], v[176:177], s[34:35], v[10:11] op_sel_hi:[1,0,1]
	v_pk_fma_f32 v[8:9], v[174:175], s[34:35], v[8:9] op_sel_hi:[1,0,1]
	v_pk_add_f32 v[178:179], v[178:179], v[194:195] op_sel_hi:[1,0] neg_lo:[0,1] neg_hi:[0,1]
	v_pk_add_f32 v[180:181], v[180:181], v[194:195] op_sel_hi:[1,0] neg_lo:[0,1] neg_hi:[0,1]
	v_pk_mul_f32 v[180:181], v[194:195], v[180:181] op_sel:[1,0]
	v_pk_mul_f32 v[178:179], v[194:195], v[178:179] op_sel:[1,0]
	v_pk_fma_f32 v[178:179], v[210:211], v[178:179], v[220:221]
	v_pk_fma_f32 v[180:181], v[212:213], v[180:181], v[222:223]
	v_pk_fma_f32 v[6:7], v[180:181], s[34:35], v[6:7] op_sel_hi:[1,0,1]
	v_pk_fma_f32 v[4:5], v[178:179], s[34:35], v[4:5] op_sel_hi:[1,0,1]
	v_add_u32_e32 v225, 0x100000, v224
	global_store_dwordx4 v225, v[16:19], s[14:15] offset:576
	v_add_u32_e32 v226, 0x120000, v224
	global_store_dwordx4 v226, v[12:15], s[14:15] offset:576
	v_add_u32_e32 v225, 0x140000, v224
	global_store_dwordx4 v225, v[8:11], s[14:15] offset:576
	v_add_u32_e32 v226, 0x160000, v224
	global_store_dwordx4 v226, v[4:7], s[14:15] offset:576
	s_and_b64 vcc, exec, s[6:7]
	s_mov_b64 s[6:7], -1
	s_cbranch_vccnz .LBB0_170
	v_readlane_b32 s6, v255, 37
	v_readlane_b32 s7, v255, 38
	s_andn2_b64 vcc, exec, s[6:7]
	s_cbranch_vccnz .LBB0_169
	s_barrier
	s_branch .LBB0_169

;     __device__ __forceinline__ void operator()(const f32x4 (&acc)[2][2][4][2], const Unit& u, int wr, int wc, int fr, int fq) const {
;         const int row0 = u.pm * BM + wr * 64 + fr; const int col0 = u.pn * BM + wc * 32 + 4 * fq;
; #pragma unroll
;         for (int bj = 0; bj < 2; ++bj)
; #pragma unroll
;             for (int n = 0; n < 2; ++n) {
;                 const int col = col0 + bj * HALF + n * 16;
;                 f32x4 gg = {1.f, 1.f, 1.f, 1.f}, bb = {0.f, 0.f, 0.f, 0.f};
;                 if (NORM) { gg = *(const f32x4*)(gam + col); bb = *(const f32x4*)(bet + col); }
; #pragma unroll
;                 for (int ai = 0; ai < 2; ++ai) {
;                     f32x4 xv[4]; f32x2 st[4];
; #pragma unroll
;                     for (int m = 0; m < 4; ++m) { xv[m] = *(const f32x4*)(X + (size_t)(row0 + ai * HALF + m * 16) * D + col);
;                         if (NORM) st[m] = *(const f32x2*)(stats + 2 * (row0 + ai * HALF + m * 16)); }
; #pragma unroll
;                     for (int m = 0; m < 4; ++m) {
;                         f32x4 x = xv[m];
;                         if (NORM) x = (x - st[m].x) * st[m].y * gg + bb;
;                         if (!dry) *(f32x4*)(X + (size_t)(row0 + ai * HALF + m * 16) * D + col) = x * ALPHA + acc[ai][bj][m][n];
.LBB0_254:
	v_lshl_add_u32 v225, s0, 8, v171
	v_lshl_or_b32 v226, s16, 8, v234
	v_lshlrev_b32_e32 v227, 3, v225
	v_lshlrev_b32_e32 v236, 2, v226
	v_lshl_add_u32 v224, v225, 13, v236
	global_load_dwordx2 v[162:163], v227, s[20:21]
	global_load_dwordx2 v[186:187], v227, s[20:21] offset:128
	global_load_dwordx2 v[188:189], v227, s[20:21] offset:256
	global_load_dwordx2 v[190:191], v227, s[20:21] offset:384
	global_load_dwordx2 v[192:193], v227, s[20:21] offset:1024
	global_load_dwordx2 v[194:195], v227, s[20:21] offset:1152
	global_load_dwordx2 v[196:197], v227, s[20:21] offset:1280
	global_load_dwordx2 v[198:199], v227, s[20:21] offset:1408
	global_load_dwordx4 v[200:203], v236, s[38:39]
	global_load_dwordx4 v[204:207], v236, s[10:11]
	global_load_dwordx4 v[210:213], v236, s[38:39] offset:64
	global_load_dwordx4 v[220:223], v236, s[10:11] offset:64
	global_load_dwordx4 v[142:145], v224, s[14:15]
	v_add_u32_e32 v226, 0x20000, v224
	global_load_dwordx4 v[146:149], v226, s[14:15]
	v_add_u32_e32 v225, 0x40000, v224
	global_load_dwordx4 v[150:153], v225, s[14:15]
	v_add_u32_e32 v226, 0x60000, v224
	global_load_dwordx4 v[154:157], v226, s[14:15]
	v_add_u32_e32 v225, 0x100000, v224
	global_load_dwordx4 v[158:161], v225, s[14:15]
	v_add_u32_e32 v226, 0x120000, v224
	global_load_dwordx4 v[174:177], v226, s[14:15]
	v_add_u32_e32 v225, 0x140000, v224
	global_load_dwordx4 v[178:181], v225, s[14:15]
	v_add_u32_e32 v226, 0x160000, v224
	global_load_dwordx4 v[182:185], v226, s[14:15]
	s_waitcnt vmcnt(4)
	v_pk_add_f32 v[142:143], v[142:143], v[162:163] op_sel_hi:[1,0] neg_lo:[0,1] neg_hi:[0,1]
	v_pk_add_f32 v[144:145], v[144:145], v[162:163] op_sel_hi:[1,0] neg_lo:[0,1] neg_hi:[0,1]
	v_pk_mul_f32 v[144:145], v[162:163], v[144:145] op_sel:[1,0]
	v_pk_mul_f32 v[142:143], v[162:163], v[142:143] op_sel:[1,0]
	v_pk_fma_f32 v[142:143], v[200:201], v[142:143], v[204:205]
	v_pk_fma_f32 v[144:145], v[202:203], v[144:145], v[206:207]
	v_pk_fma_f32 v[130:131], v[144:145], s[34:35], v[130:131] op_sel_hi:[1,0,1]
	v_pk_fma_f32 v[128:129], v[142:143], s[34:35], v[128:129] op_sel_hi:[1,0,1]
	v_pk_add_f32 v[146:147], v[146:147], v[186:187] op_sel_hi:[1,0] neg_lo:[0,1] neg_hi:[0,1]
	v_pk_add_f32 v[148:149], v[148:149], v[186:187] op_sel_hi:[1,0] neg_lo:[0,1] neg_hi:[0,1]
	v_pk_mul_f32 v[148:149], v[186:187], v[148:149] op_sel:[1,0]
	v_pk_mul_f32 v[146:147], v[186:187], v[146:147] op_sel:[1,0]
	v_pk_fma_f32 v[146:147], v[200:201], v[146:147], v[204:205]
	v_pk_fma_f32 v[148:149], v[202:203], v[148:149], v[206:207]
	v_pk_fma_f32 v[126:127], v[148:149], s[34:35], v[126:127] op_sel_hi:[1,0,1]
	v_pk_fma_f32 v[124:125], v[146:147], s[34:35], v[124:125] op_sel_hi:[1,0,1]
	v_pk_add_f32 v[150:151], v[150:151], v[188:189] op_sel_hi:[1,0] neg_lo:[0,1] neg_hi:[0,1]
	v_pk_add_f32 v[152:153], v[152:153], v[188:189] op_sel_hi:[1,0] neg_lo:[0,1] neg_hi:[0,1]
	v_pk_mul_f32 v[152:153], v[188:189], v[152:153] op_sel:[1,0]
	v_pk_mul_f32 v[150:151], v[188:189], v[150:151] op_sel:[1,0]
	v_pk_fma_f32 v[150:151], v[200:201], v[150:151], v[204:205]
	v_pk_fma_f32 v[152:153], v[202:203], v[152:153], v[206:207]
	v_pk_fma_f32 v[122:123], v[152:153], s[34:35], v[122:123] op_sel_hi:[1,0,1]
	v_pk_fma_f32 v[120:121], v[150:151], s[34:35], v[120:121] op_sel_hi:[1,0,1]
	v_pk_add_f32 v[154:155], v[154:155], v[190:191] op_sel_hi:[1,0] neg_lo:[0,1] neg_hi:[0,1]
	v_pk_add_f32 v[156:157], v[156:157], v[190:191] op_sel_hi:[1,0] neg_lo:[0,1] neg_hi:[0,1]
	v_pk_mul_f32 v[156:157], v[190:191], v[156:157] op_sel:[1,0]
	v_pk_mul_f32 v[154:155], v[190:191], v[154:155] op_sel:[1,0]
	v_pk_fma_f32 v[154:155], v[200:201], v[154:155], v[204:205]
	v_pk_fma_f32 v[156:157], v[202:203], v[156:157], v[206:207]
	v_pk_fma_f32 v[118:119], v[156:157], s[34:35], v[118:119] op_sel_hi:[1,0,1]
	v_pk_fma_f32 v[116:117], v[154:155], s[34:35], v[116:117] op_sel_hi:[1,0,1]
	global_load_dwordx4 v[142:145], v224, s[14:15] offset:64
	v_add_u32_e32 v226, 0x20000, v224
	global_load_dwordx4 v[146:149], v226, s[14:15] offset:64
	v_add_u32_e32 v225, 0x40000, v224
	global_load_dwordx4 v[150:153], v225, s[14:15] offset:64
	v_add_u32_e32 v226, 0x60000, v224
	global_load_dwordx4 v[154:157], v226, s[14:15] offset:64
	global_store_dwordx4 v224, v[128:131], s[14:15]
	v_add_u32_e32 v226, 0x20000, v224
	global_store_dwordx4 v226, v[124:127], s[14:15]
	v_add_u32_e32 v225, 0x40000, v224
	global_store_dwordx4 v225, v[120:123], s[14:15]
	v_add_u32_e32 v226, 0x60000, v224
	global_store_dwordx4 v226, v[116:119], s[14:15]
	s_waitcnt vmcnt(8)
;     __device__ __forceinline__ void operator()(const f32x4 (&acc)[2][2][4][2], const Unit& u, int wr, int wc, int fr, int fq) const {
;     ...
;             for (int n = 0; n < 2; ++n) {
;                 const int col = col0 + bj * HALF + n * 16;
;                 f32x4 gg = {1.f, 1.f, 1.f, 1.f}, bb = {0.f, 0.f, 0.f, 0.f};
;                 if (NORM) { gg = *(const f32x4*)(gam + col); bb = *(const f32x4*)(bet + col); }
; #pragma unroll
;                 for (int ai = 0; ai < 2; ++ai) {
;                     f32x4 xv[4]; f32x2 st[4];
; #pragma unroll
;                     for (int m = 0; m < 4; ++m) { xv[m] = *(const f32x4*)(X + (size_t)(row0 + ai * HALF + m * 16) * D + col);
;                         if (NORM) st[m] = *(const f32x2*)(stats + 2 * (row0 + ai * HALF + m * 16)); }
; #pragma unroll
;                     for (int m = 0; m < 4; ++m) {
;                         f32x4 x = xv[m];
;                         if (NORM) x = (x - st[m].x) * st[m].y * gg + bb;
;                         if (!dry) *(f32x4*)(X + (size_t)(row0 + ai * HALF + m * 16) * D + col) = x * ALPHA + acc[ai][bj][m][n];
;                     }
	v_pk_add_f32 v[158:159], v[158:159], v[192:193] op_sel_hi:[1,0] neg_lo:[0,1] neg_hi:[0,1]
	v_pk_add_f32 v[160:161], v[160:161], v[192:193] op_sel_hi:[1,0] neg_lo:[0,1] neg_hi:[0,1]
	v_pk_mul_f32 v[160:161], v[192:193], v[160:161] op_sel:[1,0]
	v_pk_mul_f32 v[158:159], v[192:193], v[158:159] op_sel:[1,0]
	v_pk_fma_f32 v[158:159], v[200:201], v[158:159], v[204:205]
	v_pk_fma_f32 v[160:161], v[202:203], v[160:161], v[206:207]
	v_pk_fma_f32 v[114:115], v[160:161], s[34:35], v[114:115] op_sel_hi:[1,0,1]
	v_pk_fma_f32 v[112:113], v[158:159], s[34:35], v[112:113] op_sel_hi:[1,0,1]
	v_pk_add_f32 v[174:175], v[174:175], v[194:195] op_sel_hi:[1,0] neg_lo:[0,1] neg_hi:[0,1]
	v_pk_add_f32 v[176:177], v[176:177], v[194:195] op_sel_hi:[1,0] neg_lo:[0,1] neg_hi:[0,1]
	v_pk_mul_f32 v[176:177], v[194:195], v[176:177] op_sel:[1,0]
	v_pk_mul_f32 v[174:175], v[194:195], v[174:175] op_sel:[1,0]
	v_pk_fma_f32 v[174:175], v[200:201], v[174:175], v[204:205]
	v_pk_fma_f32 v[176:177], v[202:203], v[176:177], v[206:207]
	v_pk_fma_f32 v[110:111], v[176:177], s[34:35], v[110:111] op_sel_hi:[1,0,1]
	v_pk_fma_f32 v[108:109], v[174:175], s[34:35], v[108:109] op_sel_hi:[1,0,1]
	v_pk_add_f32 v[178:179], v[178:179], v[196:197] op_sel_hi:[1,0] neg_lo:[0,1] neg_hi:[0,1]
	v_pk_add_f32 v[180:181], v[180:181], v[196:197] op_sel_hi:[1,0] neg_lo:[0,1] neg_hi:[0,1]
	v_pk_mul_f32 v[180:181], v[196:197], v[180:181] op_sel:[1,0]
	v_pk_mul_f32 v[178:179], v[196:197], v[178:179] op_sel:[1,0]
	v_pk_fma_f32 v[178:179], v[200:201], v[178:179], v[204:205]
	v_pk_fma_f32 v[180:181], v[202:203], v[180:181], v[206:207]
	v_pk_fma_f32 v[106:107], v[180:181], s[34:35], v[106:107] op_sel_hi:[1,0,1]
	v_pk_fma_f32 v[104:105], v[178:179], s[34:35], v[104:105] op_sel_hi:[1,0,1]
	v_pk_add_f32 v[182:183], v[182:183], v[198:199] op_sel_hi:[1,0] neg_lo:[0,1] neg_hi:[0,1]
	v_pk_add_f32 v[184:185], v[184:185], v[198:199] op_sel_hi:[1,0] neg_lo:[0,1] neg_hi:[0,1]
	v_pk_mul_f32 v[184:185], v[198:199], v[184:185] op_sel:[1,0]
	v_pk_mul_f32 v[182:183], v[198:199], v[182:183] op_sel:[1,0]
	v_pk_fma_f32 v[182:183], v[200:201], v[182:183], v[204:205]
	v_pk_fma_f32 v[184:185], v[202:203], v[184:185], v[206:207]
	v_pk_fma_f32 v[102:103], v[184:185], s[34:35], v[102:103] op_sel_hi:[1,0,1]
	v_pk_fma_f32 v[100:101], v[182:183], s[34:35], v[100:101] op_sel_hi:[1,0,1]
	global_load_dwordx4 v[200:203], v236, s[38:39] offset:512
	global_load_dwordx4 v[204:207], v236, s[10:11] offset:512
	v_add_u32_e32 v225, 0x100000, v224
	global_load_dwordx4 v[158:161], v225, s[14:15] offset:64
	v_add_u32_e32 v226, 0x120000, v224
	global_load_dwordx4 v[174:177], v226, s[14:15] offset:64
	v_add_u32_e32 v225, 0x140000, v224
	global_load_dwordx4 v[178:181], v225, s[14:15] offset:64
	v_add_u32_e32 v226, 0x160000, v224
	global_load_dwordx4 v[182:185], v226, s[14:15] offset:64
	v_add_u32_e32 v225, 0x100000, v224
	global_store_dwordx4 v225, v[112:115], s[14:15]
	v_add_u32_e32 v226, 0x120000, v224
	global_store_dwordx4 v226, v[108:111], s[14:15]
	v_add_u32_e32 v225, 0x140000, v224
	global_store_dwordx4 v225, v[104:107], s[14:15]
	v_add_u32_e32 v226, 0x160000, v224
	global_store_dwordx4 v226, v[100:103], s[14:15]
	s_waitcnt vmcnt(14)
	v_pk_add_f32 v[142:143], v[142:143], v[162:163] op_sel_hi:[1,0] neg_lo:[0,1] neg_hi:[0,1]
	v_pk_add_f32 v[144:145], v[144:145], v[162:163] op_sel_hi:[1,0] neg_lo:[0,1] neg_hi:[0,1]
	v_pk_mul_f32 v[144:145], v[162:163], v[144:145] op_sel:[1,0]
	v_pk_mul_f32 v[142:143], v[162:163], v[142:143] op_sel:[1,0]
	v_pk_fma_f32 v[142:143], v[210:211], v[142:143], v[220:221]
	v_pk_fma_f32 v[144:145], v[212:213], v[144:145], v[222:223]
	v_pk_fma_f32 v[98:99], v[144:145], s[34:35], v[98:99] op_sel_hi:[1,0,1]
	v_pk_fma_f32 v[96:97], v[142:143], s[34:35], v[96:97] op_sel_hi:[1,0,1]
	v_pk_add_f32 v[146:147], v[146:147], v[186:187] op_sel_hi:[1,0] neg_lo:[0,1] neg_hi:[0,1]
	v_pk_add_f32 v[148:149], v[148:149], v[186:187] op_sel_hi:[1,0] neg_lo:[0,1] neg_hi:[0,1]
	v_pk_mul_f32 v[148:149], v[186:187], v[148:149] op_sel:[1,0]
	v_pk_mul_f32 v[146:147], v[186:187], v[146:147] op_sel:[1,0]
	v_pk_fma_f32 v[146:147], v[210:211], v[146:147], v[220:221]
	v_pk_fma_f32 v[148:149], v[212:213], v[148:149], v[222:223]
	v_pk_fma_f32 v[94:95], v[148:149], s[34:35], v[94:95] op_sel_hi:[1,0,1]
	v_pk_fma_f32 v[92:93], v[146:147], s[34:35], v[92:93] op_sel_hi:[1,0,1]
	v_pk_add_f32 v[150:151], v[150:151], v[188:189] op_sel_hi:[1,0] neg_lo:[0,1] neg_hi:[0,1]
	v_pk_add_f32 v[152:153], v[152:153], v[188:189] op_sel_hi:[1,0] neg_lo:[0,1] neg_hi:[0,1]
	v_pk_mul_f32 v[152:153], v[188:189], v[152:153] op_sel:[1,0]
	v_pk_mul_f32 v[150:151], v[188:189], v[150:151] op_sel:[1,0]
	v_pk_fma_f32 v[150:151], v[210:211], v[150:151], v[220:221]
	v_pk_fma_f32 v[152:153], v[212:213], v[152:153], v[222:223]
	v_pk_fma_f32 v[90:91], v[152:153], s[34:35], v[90:91] op_sel_hi:[1,0,1]
	v_pk_fma_f32 v[88:89], v[150:151], s[34:35], v[88:89] op_sel_hi:[1,0,1]
	v_pk_add_f32 v[154:155], v[154:155], v[190:191] op_sel_hi:[1,0] neg_lo:[0,1] neg_hi:[0,1]
	v_pk_add_f32 v[156:157], v[156:157], v[190:191] op_sel_hi:[1,0] neg_lo:[0,1] neg_hi:[0,1]
	v_pk_mul_f32 v[156:157], v[190:191], v[156:157] op_sel:[1,0]
	v_pk_mul_f32 v[154:155], v[190:191], v[154:155] op_sel:[1,0]
	v_pk_fma_f32 v[154:155], v[210:211], v[154:155], v[220:221]
	v_pk_fma_f32 v[156:157], v[212:213], v[156:157], v[222:223]
	v_pk_fma_f32 v[86:87], v[156:157], s[34:35], v[86:87] op_sel_hi:[1,0,1]
	v_pk_fma_f32 v[84:85], v[154:155], s[34:35], v[84:85] op_sel_hi:[1,0,1]
	global_load_dwordx4 v[142:145], v224, s[14:15] offset:512
	v_add_u32_e32 v226, 0x20000, v224
	global_load_dwordx4 v[146:149], v226, s[14:15] offset:512
	v_add_u32_e32 v225, 0x40000, v224
	global_load_dwordx4 v[150:153], v225, s[14:15] offset:512
	v_add_u32_e32 v226, 0x60000, v224
	global_load_dwordx4 v[154:157], v226, s[14:15] offset:512
	global_store_dwordx4 v224, v[96:99], s[14:15] offset:64
	v_add_u32_e32 v226, 0x20000, v224
	global_store_dwordx4 v226, v[92:95], s[14:15] offset:64
	v_add_u32_e32 v225, 0x40000, v224
	global_store_dwordx4 v225, v[88:91], s[14:15] offset:64
	v_add_u32_e32 v226, 0x60000, v224
	global_store_dwordx4 v226, v[84:87], s[14:15] offset:64
	s_waitcnt vmcnt(12)
;     __device__ __forceinline__ void operator()(const f32x4 (&acc)[2][2][4][2], const Unit& u, int wr, int wc, int fr, int fq) const {
;     ...
;             for (int n = 0; n < 2; ++n) {
;                 const int col = col0 + bj * HALF + n * 16;
;                 f32x4 gg = {1.f, 1.f, 1.f, 1.f}, bb = {0.f, 0.f, 0.f, 0.f};
;                 if (NORM) { gg = *(const f32x4*)(gam + col); bb = *(const f32x4*)(bet + col); }
; #pragma unroll
;                 for (int ai = 0; ai < 2; ++ai) {
;                     f32x4 xv[4]; f32x2 st[4];
; #pragma unroll
;                     for (int m = 0; m < 4; ++m) { xv[m] = *(const f32x4*)(X + (size_t)(row0 + ai * HALF + m * 16) * D + col);
;                         if (NORM) st[m] = *(const f32x2*)(stats + 2 * (row0 + ai * HALF + m * 16)); }
; #pragma unroll
;                     for (int m = 0; m < 4; ++m) {
;                         f32x4 x = xv[m];
;                         if (NORM) x = (x - st[m].x) * st[m].y * gg + bb;
;                         if (!dry) *(f32x4*)(X + (size_t)(row0 + ai * HALF + m * 16) * D + col) = x * ALPHA + acc[ai][bj][m][n];
;                     }
	v_pk_add_f32 v[158:159], v[158:159], v[192:193] op_sel_hi:[1,0] neg_lo:[0,1] neg_hi:[0,1]
	v_pk_add_f32 v[160:161], v[160:161], v[192:193] op_sel_hi:[1,0] neg_lo:[0,1] neg_hi:[0,1]
	v_pk_mul_f32 v[160:161], v[192:193], v[160:161] op_sel:[1,0]
	v_pk_mul_f32 v[158:159], v[192:193], v[158:159] op_sel:[1,0]
	v_pk_fma_f32 v[158:159], v[210:211], v[158:159], v[220:221]
	v_pk_fma_f32 v[160:161], v[212:213], v[160:161], v[222:223]
	v_pk_fma_f32 v[82:83], v[160:161], s[34:35], v[82:83] op_sel_hi:[1,0,1]
	v_pk_fma_f32 v[80:81], v[158:159], s[34:35], v[80:81] op_sel_hi:[1,0,1]
	v_pk_add_f32 v[174:175], v[174:175], v[194:195] op_sel_hi:[1,0] neg_lo:[0,1] neg_hi:[0,1]
	v_pk_add_f32 v[176:177], v[176:177], v[194:195] op_sel_hi:[1,0] neg_lo:[0,1] neg_hi:[0,1]
	v_pk_mul_f32 v[176:177], v[194:195], v[176:177] op_sel:[1,0]
	v_pk_mul_f32 v[174:175], v[194:195], v[174:175] op_sel:[1,0]
	v_pk_fma_f32 v[174:175], v[210:211], v[174:175], v[220:221]
	v_pk_fma_f32 v[176:177], v[212:213], v[176:177], v[222:223]
	v_pk_fma_f32 v[78:79], v[176:177], s[34:35], v[78:79] op_sel_hi:[1,0,1]
	v_pk_fma_f32 v[76:77], v[174:175], s[34:35], v[76:77] op_sel_hi:[1,0,1]
	v_pk_add_f32 v[178:179], v[178:179], v[196:197] op_sel_hi:[1,0] neg_lo:[0,1] neg_hi:[0,1]
	v_pk_add_f32 v[180:181], v[180:181], v[196:197] op_sel_hi:[1,0] neg_lo:[0,1] neg_hi:[0,1]
	v_pk_mul_f32 v[180:181], v[196:197], v[180:181] op_sel:[1,0]
	v_pk_mul_f32 v[178:179], v[196:197], v[178:179] op_sel:[1,0]
	v_pk_fma_f32 v[178:179], v[210:211], v[178:179], v[220:221]
	v_pk_fma_f32 v[180:181], v[212:213], v[180:181], v[222:223]
	v_pk_fma_f32 v[74:75], v[180:181], s[34:35], v[74:75] op_sel_hi:[1,0,1]
	v_pk_fma_f32 v[72:73], v[178:179], s[34:35], v[72:73] op_sel_hi:[1,0,1]
	v_pk_add_f32 v[182:183], v[182:183], v[198:199] op_sel_hi:[1,0] neg_lo:[0,1] neg_hi:[0,1]
	v_pk_add_f32 v[184:185], v[184:185], v[198:199] op_sel_hi:[1,0] neg_lo:[0,1] neg_hi:[0,1]
	v_pk_mul_f32 v[184:185], v[198:199], v[184:185] op_sel:[1,0]
	v_pk_mul_f32 v[182:183], v[198:199], v[182:183] op_sel:[1,0]
	v_pk_fma_f32 v[182:183], v[210:211], v[182:183], v[220:221]
	v_pk_fma_f32 v[184:185], v[212:213], v[184:185], v[222:223]
	v_pk_fma_f32 v[70:71], v[184:185], s[34:35], v[70:71] op_sel_hi:[1,0,1]
	v_pk_fma_f32 v[68:69], v[182:183], s[34:35], v[68:69] op_sel_hi:[1,0,1]
	global_load_dwordx4 v[210:213], v236, s[38:39] offset:576
	global_load_dwordx4 v[220:223], v236, s[10:11] offset:576
	v_add_u32_e32 v225, 0x100000, v224
	global_load_dwordx4 v[158:161], v225, s[14:15] offset:512
	v_add_u32_e32 v226, 0x120000, v224
	global_load_dwordx4 v[174:177], v226, s[14:15] offset:512
	v_add_u32_e32 v225, 0x140000, v224
	global_load_dwordx4 v[178:181], v225, s[14:15] offset:512
	v_add_u32_e32 v226, 0x160000, v224
	global_load_dwordx4 v[182:185], v226, s[14:15] offset:512
	v_add_u32_e32 v225, 0x100000, v224
	global_store_dwordx4 v225, v[80:83], s[14:15] offset:64
	v_add_u32_e32 v226, 0x120000, v224
	global_store_dwordx4 v226, v[76:79], s[14:15] offset:64
	v_add_u32_e32 v225, 0x140000, v224
	global_store_dwordx4 v225, v[72:75], s[14:15] offset:64
	v_add_u32_e32 v226, 0x160000, v224
	global_store_dwordx4 v226, v[68:71], s[14:15] offset:64
	s_waitcnt vmcnt(14)
	v_pk_add_f32 v[142:143], v[142:143], v[162:163] op_sel_hi:[1,0] neg_lo:[0,1] neg_hi:[0,1]
	v_pk_add_f32 v[144:145], v[144:145], v[162:163] op_sel_hi:[1,0] neg_lo:[0,1] neg_hi:[0,1]
	v_pk_mul_f32 v[144:145], v[162:163], v[144:145] op_sel:[1,0]
	v_pk_mul_f32 v[142:143], v[162:163], v[142:143] op_sel:[1,0]
	v_pk_fma_f32 v[142:143], v[200:201], v[142:143], v[204:205]
	v_pk_fma_f32 v[144:145], v[202:203], v[144:145], v[206:207]
	v_pk_fma_f32 v[66:67], v[144:145], s[34:35], v[66:67] op_sel_hi:[1,0,1]
	v_pk_fma_f32 v[64:65], v[142:143], s[34:35], v[64:65] op_sel_hi:[1,0,1]
	v_pk_add_f32 v[146:147], v[146:147], v[186:187] op_sel_hi:[1,0] neg_lo:[0,1] neg_hi:[0,1]
	v_pk_add_f32 v[148:149], v[148:149], v[186:187] op_sel_hi:[1,0] neg_lo:[0,1] neg_hi:[0,1]
	v_pk_mul_f32 v[148:149], v[186:187], v[148:149] op_sel:[1,0]
	v_pk_mul_f32 v[146:147], v[186:187], v[146:147] op_sel:[1,0]
	v_pk_fma_f32 v[146:147], v[200:201], v[146:147], v[204:205]
	v_pk_fma_f32 v[148:149], v[202:203], v[148:149], v[206:207]
	v_pk_fma_f32 v[62:63], v[148:149], s[34:35], v[62:63] op_sel_hi:[1,0,1]
	v_pk_fma_f32 v[60:61], v[146:147], s[34:35], v[60:61] op_sel_hi:[1,0,1]
	v_pk_add_f32 v[150:151], v[150:151], v[188:189] op_sel_hi:[1,0] neg_lo:[0,1] neg_hi:[0,1]
	v_pk_add_f32 v[152:153], v[152:153], v[188:189] op_sel_hi:[1,0] neg_lo:[0,1] neg_hi:[0,1]
	v_pk_mul_f32 v[152:153], v[188:189], v[152:153] op_sel:[1,0]
	v_pk_mul_f32 v[150:151], v[188:189], v[150:151] op_sel:[1,0]
	v_pk_fma_f32 v[150:151], v[200:201], v[150:151], v[204:205]
	v_pk_fma_f32 v[152:153], v[202:203], v[152:153], v[206:207]
	v_pk_fma_f32 v[58:59], v[152:153], s[34:35], v[58:59] op_sel_hi:[1,0,1]
	v_pk_fma_f32 v[56:57], v[150:151], s[34:35], v[56:57] op_sel_hi:[1,0,1]
	v_pk_add_f32 v[154:155], v[154:155], v[190:191] op_sel_hi:[1,0] neg_lo:[0,1] neg_hi:[0,1]
	v_pk_add_f32 v[156:157], v[156:157], v[190:191] op_sel_hi:[1,0] neg_lo:[0,1] neg_hi:[0,1]
	v_pk_mul_f32 v[156:157], v[190:191], v[156:157] op_sel:[1,0]
	v_pk_mul_f32 v[154:155], v[190:191], v[154:155] op_sel:[1,0]
	v_pk_fma_f32 v[154:155], v[200:201], v[154:155], v[204:205]
	v_pk_fma_f32 v[156:157], v[202:203], v[156:157], v[206:207]
	v_pk_fma_f32 v[54:55], v[156:157], s[34:35], v[54:55] op_sel_hi:[1,0,1]
	v_pk_fma_f32 v[52:53], v[154:155], s[34:35], v[52:53] op_sel_hi:[1,0,1]
	global_load_dwordx4 v[142:145], v224, s[14:15] offset:576
	v_add_u32_e32 v226, 0x20000, v224
	global_load_dwordx4 v[146:149], v226, s[14:15] offset:576
	v_add_u32_e32 v225, 0x40000, v224
	global_load_dwordx4 v[150:153], v225, s[14:15] offset:576
	v_add_u32_e32 v226, 0x60000, v224
	global_load_dwordx4 v[154:157], v226, s[14:15] offset:576
	global_store_dwordx4 v224, v[64:67], s[14:15] offset:512
	v_add_u32_e32 v226, 0x20000, v224
	global_store_dwordx4 v226, v[60:63], s[14:15] offset:512
	v_add_u32_e32 v225, 0x40000, v224
	global_store_dwordx4 v225, v[56:59], s[14:15] offset:512
	v_add_u32_e32 v226, 0x60000, v224
	global_store_dwordx4 v226, v[52:55], s[14:15] offset:512
	s_waitcnt vmcnt(12)
;     __device__ __forceinline__ void operator()(const f32x4 (&acc)[2][2][4][2], const Unit& u, int wr, int wc, int fr, int fq) const {
;     ...
;             for (int n = 0; n < 2; ++n) {
;                 const int col = col0 + bj * HALF + n * 16;
;                 f32x4 gg = {1.f, 1.f, 1.f, 1.f}, bb = {0.f, 0.f, 0.f, 0.f};
;                 if (NORM) { gg = *(const f32x4*)(gam + col); bb = *(const f32x4*)(bet + col); }
; #pragma unroll
;                 for (int ai = 0; ai < 2; ++ai) {
;                     f32x4 xv[4]; f32x2 st[4];
; #pragma unroll
;                     for (int m = 0; m < 4; ++m) { xv[m] = *(const f32x4*)(X + (size_t)(row0 + ai * HALF + m * 16) * D + col);
;                         if (NORM) st[m] = *(const f32x2*)(stats + 2 * (row0 + ai * HALF + m * 16)); }
; #pragma unroll
;                     for (int m = 0; m < 4; ++m) {
;                         f32x4 x = xv[m];
;                         if (NORM) x = (x - st[m].x) * st[m].y * gg + bb;
;                         if (!dry) *(f32x4*)(X + (size_t)(row0 + ai * HALF + m * 16) * D + col) = x * ALPHA + acc[ai][bj][m][n];
;                     }
	v_pk_add_f32 v[158:159], v[158:159], v[192:193] op_sel_hi:[1,0] neg_lo:[0,1] neg_hi:[0,1]
	v_pk_add_f32 v[160:161], v[160:161], v[192:193] op_sel_hi:[1,0] neg_lo:[0,1] neg_hi:[0,1]
	v_pk_mul_f32 v[160:161], v[192:193], v[160:161] op_sel:[1,0]
	v_pk_mul_f32 v[158:159], v[192:193], v[158:159] op_sel:[1,0]
	v_pk_fma_f32 v[158:159], v[200:201], v[158:159], v[204:205]
	v_pk_fma_f32 v[160:161], v[202:203], v[160:161], v[206:207]
	v_pk_fma_f32 v[50:51], v[160:161], s[34:35], v[50:51] op_sel_hi:[1,0,1]
	v_pk_fma_f32 v[48:49], v[158:159], s[34:35], v[48:49] op_sel_hi:[1,0,1]
	v_pk_add_f32 v[174:175], v[174:175], v[194:195] op_sel_hi:[1,0] neg_lo:[0,1] neg_hi:[0,1]
	v_pk_add_f32 v[176:177], v[176:177], v[194:195] op_sel_hi:[1,0] neg_lo:[0,1] neg_hi:[0,1]
	v_pk_mul_f32 v[176:177], v[194:195], v[176:177] op_sel:[1,0]
	v_pk_mul_f32 v[174:175], v[194:195], v[174:175] op_sel:[1,0]
	v_pk_fma_f32 v[174:175], v[200:201], v[174:175], v[204:205]
	v_pk_fma_f32 v[176:177], v[202:203], v[176:177], v[206:207]
	v_pk_fma_f32 v[46:47], v[176:177], s[34:35], v[46:47] op_sel_hi:[1,0,1]
	v_pk_fma_f32 v[44:45], v[174:175], s[34:35], v[44:45] op_sel_hi:[1,0,1]
	v_pk_add_f32 v[178:179], v[178:179], v[196:197] op_sel_hi:[1,0] neg_lo:[0,1] neg_hi:[0,1]
	v_pk_add_f32 v[180:181], v[180:181], v[196:197] op_sel_hi:[1,0] neg_lo:[0,1] neg_hi:[0,1]
	v_pk_mul_f32 v[180:181], v[196:197], v[180:181] op_sel:[1,0]
	v_pk_mul_f32 v[178:179], v[196:197], v[178:179] op_sel:[1,0]
	v_pk_fma_f32 v[178:179], v[200:201], v[178:179], v[204:205]
	v_pk_fma_f32 v[180:181], v[202:203], v[180:181], v[206:207]
	v_pk_fma_f32 v[42:43], v[180:181], s[34:35], v[42:43] op_sel_hi:[1,0,1]
	v_pk_fma_f32 v[40:41], v[178:179], s[34:35], v[40:41] op_sel_hi:[1,0,1]
	v_pk_add_f32 v[182:183], v[182:183], v[198:199] op_sel_hi:[1,0] neg_lo:[0,1] neg_hi:[0,1]
	v_pk_add_f32 v[184:185], v[184:185], v[198:199] op_sel_hi:[1,0] neg_lo:[0,1] neg_hi:[0,1]
	v_pk_mul_f32 v[184:185], v[198:199], v[184:185] op_sel:[1,0]
	v_pk_mul_f32 v[182:183], v[198:199], v[182:183] op_sel:[1,0]
	v_pk_fma_f32 v[182:183], v[200:201], v[182:183], v[204:205]
	v_pk_fma_f32 v[184:185], v[202:203], v[184:185], v[206:207]
	v_pk_fma_f32 v[38:39], v[184:185], s[34:35], v[38:39] op_sel_hi:[1,0,1]
	v_pk_fma_f32 v[36:37], v[182:183], s[34:35], v[36:37] op_sel_hi:[1,0,1]
	v_add_u32_e32 v225, 0x100000, v224
	global_load_dwordx4 v[158:161], v225, s[14:15] offset:576
	v_add_u32_e32 v226, 0x120000, v224
	global_load_dwordx4 v[174:177], v226, s[14:15] offset:576
	v_add_u32_e32 v225, 0x140000, v224
	global_load_dwordx4 v[178:181], v225, s[14:15] offset:576
	v_add_u32_e32 v226, 0x160000, v224
	global_load_dwordx4 v[182:185], v226, s[14:15] offset:576
	v_add_u32_e32 v225, 0x100000, v224
	global_store_dwordx4 v225, v[48:51], s[14:15] offset:512
	v_add_u32_e32 v226, 0x120000, v224
	global_store_dwordx4 v226, v[44:47], s[14:15] offset:512
	v_add_u32_e32 v225, 0x140000, v224
	global_store_dwordx4 v225, v[40:43], s[14:15] offset:512
	v_add_u32_e32 v226, 0x160000, v224
	global_store_dwordx4 v226, v[36:39], s[14:15] offset:512
	s_waitcnt vmcnt(12)
; #define PG8_BAR __builtin_amdgcn_s_barrier()
; template <class Epi, class Sched>
; __device__ __forceinline__ void gemm_phase(LAS unsigned char* lds, const Gemm g, const Sched& S, const Epi& E, const int tid) {
;     ...
;         if (wr == 0) PG8_BAR;
;         E(acc, cur, wr, wc, fr, fq);
;         if (!has_next) break;
; #pragma unroll
;         for (int a = 0; a < 2; ++a)
; #pragma unroll
;             for (int b = 0; b < 2; ++b)
; #pragma unroll
;                 for (int m = 0; m < 4; ++m)
; #pragma unroll
;                     for (int n = 0; n < 2; ++n) acc[a][b][m][n] = (f32x4){0.f, 0.f, 0.f, 0.f};
;         cur = nxt; cA = nA; cB = nB; ++ui;
;         if (wr == 1) PG8_BAR;
;     __device__ __forceinline__ void operator()(const f32x4 (&acc)[2][2][4][2], const Unit& u, int wr, int wc, int fr, int fq) const {
;     ...
;             for (int n = 0; n < 2; ++n) {
;                 const int col = col0 + bj * HALF + n * 16;
;                 f32x4 gg = {1.f, 1.f, 1.f, 1.f}, bb = {0.f, 0.f, 0.f, 0.f};
;                 if (NORM) { gg = *(const f32x4*)(gam + col); bb = *(const f32x4*)(bet + col); }
; #pragma unroll
;                 for (int ai = 0; ai < 2; ++ai) {
;                     f32x4 xv[4]; f32x2 st[4];
; #pragma unroll
;                     for (int m = 0; m < 4; ++m) { xv[m] = *(const f32x4*)(X + (size_t)(row0 + ai * HALF + m * 16) * D + col);
;                         if (NORM) st[m] = *(const f32x2*)(stats + 2 * (row0 + ai * HALF + m * 16)); }
; #pragma unroll
;                     for (int m = 0; m < 4; ++m) {
;                         f32x4 x = xv[m];
;                         if (NORM) x = (x - st[m].x) * st[m].y * gg + bb;
;                         if (!dry) *(f32x4*)(X + (size_t)(row0 + ai * HALF + m * 16) * D + col) = x * ALPHA + acc[ai][bj][m][n];
;                     }
	v_pk_add_f32 v[142:143], v[142:143], v[162:163] op_sel_hi:[1,0] neg_lo:[0,1] neg_hi:[0,1]
	v_pk_add_f32 v[144:145], v[144:145], v[162:163] op_sel_hi:[1,0] neg_lo:[0,1] neg_hi:[0,1]
	v_pk_mul_f32 v[144:145], v[162:163], v[144:145] op_sel:[1,0]
	v_pk_mul_f32 v[142:143], v[162:163], v[142:143] op_sel:[1,0]
	v_pk_fma_f32 v[142:143], v[210:211], v[142:143], v[220:221]
	v_pk_fma_f32 v[144:145], v[212:213], v[144:145], v[222:223]
	v_pk_fma_f32 v[34:35], v[144:145], s[34:35], v[34:35] op_sel_hi:[1,0,1]
	v_pk_fma_f32 v[32:33], v[142:143], s[34:35], v[32:33] op_sel_hi:[1,0,1]
	v_pk_add_f32 v[146:147], v[146:147], v[186:187] op_sel_hi:[1,0] neg_lo:[0,1] neg_hi:[0,1]
	v_pk_add_f32 v[148:149], v[148:149], v[186:187] op_sel_hi:[1,0] neg_lo:[0,1] neg_hi:[0,1]
	v_pk_mul_f32 v[148:149], v[186:187], v[148:149] op_sel:[1,0]
	v_pk_mul_f32 v[146:147], v[186:187], v[146:147] op_sel:[1,0]
	v_pk_fma_f32 v[146:147], v[210:211], v[146:147], v[220:221]
	v_pk_fma_f32 v[148:149], v[212:213], v[148:149], v[222:223]
	v_pk_fma_f32 v[30:31], v[148:149], s[34:35], v[30:31] op_sel_hi:[1,0,1]
	v_pk_fma_f32 v[28:29], v[146:147], s[34:35], v[28:29] op_sel_hi:[1,0,1]
	v_pk_add_f32 v[150:151], v[150:151], v[188:189] op_sel_hi:[1,0] neg_lo:[0,1] neg_hi:[0,1]
	v_pk_add_f32 v[152:153], v[152:153], v[188:189] op_sel_hi:[1,0] neg_lo:[0,1] neg_hi:[0,1]
	v_pk_mul_f32 v[152:153], v[188:189], v[152:153] op_sel:[1,0]
	v_pk_mul_f32 v[150:151], v[188:189], v[150:151] op_sel:[1,0]
	v_pk_fma_f32 v[150:151], v[210:211], v[150:151], v[220:221]
	v_pk_fma_f32 v[152:153], v[212:213], v[152:153], v[222:223]
	v_pk_fma_f32 v[26:27], v[152:153], s[34:35], v[26:27] op_sel_hi:[1,0,1]
	v_pk_fma_f32 v[24:25], v[150:151], s[34:35], v[24:25] op_sel_hi:[1,0,1]
	v_pk_add_f32 v[154:155], v[154:155], v[190:191] op_sel_hi:[1,0] neg_lo:[0,1] neg_hi:[0,1]
	v_pk_add_f32 v[156:157], v[156:157], v[190:191] op_sel_hi:[1,0] neg_lo:[0,1] neg_hi:[0,1]
	v_pk_mul_f32 v[156:157], v[190:191], v[156:157] op_sel:[1,0]
	v_pk_mul_f32 v[154:155], v[190:191], v[154:155] op_sel:[1,0]
	v_pk_fma_f32 v[154:155], v[210:211], v[154:155], v[220:221]
	v_pk_fma_f32 v[156:157], v[212:213], v[156:157], v[222:223]
	v_pk_fma_f32 v[22:23], v[156:157], s[34:35], v[22:23] op_sel_hi:[1,0,1]
	v_pk_fma_f32 v[20:21], v[154:155], s[34:35], v[20:21] op_sel_hi:[1,0,1]
	global_store_dwordx4 v224, v[32:35], s[14:15] offset:576
	v_add_u32_e32 v226, 0x20000, v224
	global_store_dwordx4 v226, v[28:31], s[14:15] offset:576
	v_add_u32_e32 v225, 0x40000, v224
	global_store_dwordx4 v225, v[24:27], s[14:15] offset:576
	v_add_u32_e32 v226, 0x60000, v224
	global_store_dwordx4 v226, v[20:23], s[14:15] offset:576
	s_waitcnt vmcnt(8)
	v_pk_add_f32 v[158:159], v[158:159], v[192:193] op_sel_hi:[1,0] neg_lo:[0,1] neg_hi:[0,1]
	v_pk_add_f32 v[160:161], v[160:161], v[192:193] op_sel_hi:[1,0] neg_lo:[0,1] neg_hi:[0,1]
	v_pk_mul_f32 v[160:161], v[192:193], v[160:161] op_sel:[1,0]
	v_pk_mul_f32 v[158:159], v[192:193], v[158:159] op_sel:[1,0]
	v_pk_fma_f32 v[158:159], v[210:211], v[158:159], v[220:221]
	v_pk_fma_f32 v[160:161], v[212:213], v[160:161], v[222:223]
	v_pk_fma_f32 v[18:19], v[160:161], s[34:35], v[18:19] op_sel_hi:[1,0,1]
	v_pk_fma_f32 v[16:17], v[158:159], s[34:35], v[16:17] op_sel_hi:[1,0,1]
	v_pk_add_f32 v[174:175], v[174:175], v[194:195] op_sel_hi:[1,0] neg_lo:[0,1] neg_hi:[0,1]
	v_pk_add_f32 v[176:177], v[176:177], v[194:195] op_sel_hi:[1,0] neg_lo:[0,1] neg_hi:[0,1]
	v_pk_mul_f32 v[176:177], v[194:195], v[176:177] op_sel:[1,0]
	v_pk_mul_f32 v[174:175], v[194:195], v[174:175] op_sel:[1,0]
	v_pk_fma_f32 v[174:175], v[210:211], v[174:175], v[220:221]
	v_pk_fma_f32 v[176:177], v[212:213], v[176:177], v[222:223]
	v_pk_fma_f32 v[14:15], v[176:177], s[34:35], v[14:15] op_sel_hi:[1,0,1]
	v_pk_fma_f32 v[12:13], v[174:175], s[34:35], v[12:13] op_sel_hi:[1,0,1]
	v_pk_add_f32 v[178:179], v[178:179], v[196:197] op_sel_hi:[1,0] neg_lo:[0,1] neg_hi:[0,1]
	v_pk_add_f32 v[180:181], v[180:181], v[196:197] op_sel_hi:[1,0] neg_lo:[0,1] neg_hi:[0,1]
	v_pk_mul_f32 v[180:181], v[196:197], v[180:181] op_sel:[1,0]
	v_pk_mul_f32 v[178:179], v[196:197], v[178:179] op_sel:[1,0]
	v_pk_fma_f32 v[178:179], v[210:211], v[178:179], v[220:221]
	v_pk_fma_f32 v[180:181], v[212:213], v[180:181], v[222:223]
	v_pk_fma_f32 v[10:11], v[180:181], s[34:35], v[10:11] op_sel_hi:[1,0,1]
	v_pk_fma_f32 v[8:9], v[178:179], s[34:35], v[8:9] op_sel_hi:[1,0,1]
	v_pk_add_f32 v[182:183], v[182:183], v[198:199] op_sel_hi:[1,0] neg_lo:[0,1] neg_hi:[0,1]
	v_pk_add_f32 v[184:185], v[184:185], v[198:199] op_sel_hi:[1,0] neg_lo:[0,1] neg_hi:[0,1]
	v_pk_mul_f32 v[184:185], v[198:199], v[184:185] op_sel:[1,0]
	v_pk_mul_f32 v[182:183], v[198:199], v[182:183] op_sel:[1,0]
	v_pk_fma_f32 v[182:183], v[210:211], v[182:183], v[220:221]
	v_pk_fma_f32 v[184:185], v[212:213], v[184:185], v[222:223]
	v_pk_fma_f32 v[6:7], v[184:185], s[34:35], v[6:7] op_sel_hi:[1,0,1]
	v_pk_fma_f32 v[4:5], v[182:183], s[34:35], v[4:5] op_sel_hi:[1,0,1]
	v_add_u32_e32 v225, 0x100000, v224
	global_store_dwordx4 v225, v[16:19], s[14:15] offset:576
	v_add_u32_e32 v226, 0x120000, v224
	global_store_dwordx4 v226, v[12:15], s[14:15] offset:576
	v_add_u32_e32 v225, 0x140000, v224
	global_store_dwordx4 v225, v[8:11], s[14:15] offset:576
	v_add_u32_e32 v226, 0x160000, v224
	global_store_dwordx4 v226, v[4:7], s[14:15] offset:576
	s_and_b64 vcc, exec, s[6:7]
	s_mov_b64 s[6:7], -1
	s_cbranch_vccnz .LBB0_241
	s_andn2_b64 vcc, exec, s[30:31]
	s_cbranch_vccnz .LBB0_240
	s_barrier
	s_branch .LBB0_240
